# v11 plus agent-scope write-through (sc1) stores in the P1 SwiGLU epilogue
# baseline (speedup 1.0000x reference)
; __device__ __forceinline__ unsigned cvt_pk_bf16(float lo, float hi) { unsigned r; asm volatile("v_cvt_pk_bf16_f32 %0, %1, %2" : "=v"(r) : "v"(lo), "v"(hi)); return r; }
; __device__ __forceinline__ float silu_f(float x) { return x * sigmoid_f(x); }
;     __device__ __forceinline__ void operator()(const f32x4 (&acc)[2][2][4][2], const Unit& u, int wr, int wc, int fr, int fq) const {
;         const int row0 = u.pm * BM + wr * 64 + fr, col0 = u.pn * 128 + wc * 32 + 8 * fq;
; #pragma unroll
;         for (int ai = 0; ai < 2; ++ai)
; #pragma unroll
;             for (int m = 0; m < 4; ++m) {
;                 const int row = row0 + ai * HALF + m * 16;
;                 const float r = __builtin_amdgcn_rsqf(rss[row] * (1.f / 1024.f) + NEPS);
;                 float o[8];
; #pragma unroll
;                 for (int n = 0; n < 2; ++n)
; #pragma unroll
;                     for (int e = 0; e < 4; ++e) o[4 * n + e] = silu_f(acc[ai][0][m][n][e] * r) * (acc[ai][1][m][n][e] * r);
;                 u32x4 w; w.x = cvt_pk_bf16(o[0], o[1]); w.y = cvt_pk_bf16(o[2], o[3]); w.z = cvt_pk_bf16(o[4], o[5]); w.w = cvt_pk_bf16(o[6], o[7]);
;                 *(u32x4*)(O + (size_t)row * 2816 + col0) = w;
.LBB0_134:
	v_lshl_add_u32 v140, s48, 8, v144
	v_ashrrev_i32_e32 v141, 31, v140
	v_lshl_add_u64 v[142:143], v[140:141], 2, s[4:5]
	global_load_dword v141, v[142:143], off
	v_lshl_or_b32 v152, s49, 7, v146
	v_ashrrev_i32_e32 v153, 31, v152
	v_mov_b32_e32 v156, v120
	v_mov_b32_e32 v157, v116
	v_mov_b32_e32 v116, v121
	v_lshlrev_b64 v[120:121], 1, v[152:153]
	v_mov_b32_e32 v154, v126
	v_mov_b32_e32 v155, v122
	v_mov_b32_e32 v122, v127
	v_mov_b32_e32 v126, v128
	v_mov_b32_e32 v127, v124
	v_mov_b32_e32 v124, v129
	v_mov_b32_e32 v128, v118
	v_mov_b32_e32 v129, v114
	v_mov_b32_e32 v114, v119
	v_or_b32_e32 v160, 16, v140
	v_ashrrev_i32_e32 v161, 31, v160
	v_lshl_add_u64 v[164:165], v[160:161], 2, s[4:5]
	v_mov_b64_e32 v[118:119], s[60:61]
	v_mad_i64_i32 v[158:159], s[24:25], v140, s47, v[118:119]
	v_lshl_add_u64 v[158:159], v[158:159], 0, v[120:121]
	s_andn2_b64 vcc, exec, s[6:7]
	s_mov_b64 s[6:7], -1
	s_waitcnt vmcnt(0)
	v_fmamk_f32 v141, v141, 0x3a800000, v150
	v_rsq_f32_e32 v152, v141
	s_nop 0
	v_pk_mul_f32 v[116:117], v[116:117], v[152:153] op_sel_hi:[1,0]
	v_pk_mul_f32 v[154:155], v[154:155], v[152:153] op_sel_hi:[1,0]
	v_pk_mul_f32 v[122:123], v[122:123], v[152:153] op_sel_hi:[1,0]
	v_pk_mul_f32 v[126:127], v[126:127], v[152:153] op_sel_hi:[1,0]
	v_pk_mul_f32 v[124:125], v[124:125], v[152:153] op_sel_hi:[1,0]
	v_pk_mul_f32 v[128:129], v[128:129], v[152:153] op_sel_hi:[1,0]
	v_pk_mul_f32 v[114:115], v[114:115], v[152:153] op_sel_hi:[1,0]
	v_pk_mul_f32 v[156:157], v[156:157], v[152:153] op_sel_hi:[1,0]
	v_mul_f32_e32 v167, 0xbfb8aa3b, v117
	v_mul_f32_e32 v141, 0xbfb8aa3b, v155
	v_mul_f32_e32 v151, 0xbfb8aa3b, v123
	v_mul_f32_e32 v152, 0xbfb8aa3b, v127
	v_mul_f32_e32 v153, 0xbfb8aa3b, v125
	v_mul_f32_e32 v161, 0xbfb8aa3b, v129
	v_mul_f32_e32 v163, 0xbfb8aa3b, v115
	v_mul_f32_e32 v166, 0xbfb8aa3b, v157
	v_exp_f32_e32 v167, v167
	v_exp_f32_e32 v141, v141
	v_exp_f32_e32 v151, v151
	v_exp_f32_e32 v152, v152
	v_exp_f32_e32 v153, v153
	v_exp_f32_e32 v161, v161
	v_exp_f32_e32 v163, v163
	v_exp_f32_e32 v166, v166
	v_add_f32_e32 v167, 1.0, v167
	v_add_f32_e32 v141, 1.0, v141
	v_add_f32_e32 v151, 1.0, v151
	v_add_f32_e32 v152, 1.0, v152
	v_add_f32_e32 v153, 1.0, v153
	v_add_f32_e32 v161, 1.0, v161
	v_add_f32_e32 v163, 1.0, v163
	v_add_f32_e32 v166, 1.0, v166
	v_rcp_f32_e32 v167, v167
	v_rcp_f32_e32 v141, v141
	v_rcp_f32_e32 v151, v151
	v_rcp_f32_e32 v152, v152
	v_rcp_f32_e32 v153, v153
	v_rcp_f32_e32 v161, v161
	v_rcp_f32_e32 v163, v163
	v_rcp_f32_e32 v166, v166
	v_mul_f32_e32 v117, v117, v167
	v_mul_f32_e32 v141, v155, v141
	v_mul_f32_e32 v123, v123, v151
	v_mul_f32_e32 v127, v127, v152
	v_mul_f32_e32 v125, v125, v153
	v_mul_f32_e32 v129, v129, v161
	v_mul_f32_e32 v115, v115, v163
	v_mul_f32_e32 v151, v157, v166
	v_mul_f32_e32 v117, v116, v117
	v_mul_f32_e32 v141, v154, v141
	v_mul_f32_e32 v122, v122, v123
	v_mul_f32_e32 v123, v126, v127
	v_mul_f32_e32 v124, v124, v125
	v_mul_f32_e32 v125, v128, v129
	v_mul_f32_e32 v126, v114, v115
	v_mul_f32_e32 v127, v156, v151
	v_cvt_pk_bf16_f32 v114, v141, v122
	v_cvt_pk_bf16_f32 v115, v123, v124
	v_cvt_pk_bf16_f32 v116, v125, v126
	v_cvt_pk_bf16_f32 v117, v127, v117
	global_store_dwordx4 v[158:159], v[114:117], off sc1
	global_load_dword v122, v[164:165], off
	s_nop 0
	v_mov_b32_e32 v115, v106
	v_mov_b32_e32 v106, v111
	v_mov_b32_e32 v111, v108
	v_mov_b32_e32 v108, v113
	v_mov_b32_e32 v113, v98
	v_mov_b32_e32 v98, v103
	v_mov_b32_e32 v103, v100
	v_mov_b32_e32 v100, v105
	v_mov_b32_e32 v114, v110
	v_mov_b32_e32 v110, v112
	v_mov_b32_e32 v112, v102
	v_mov_b32_e32 v102, v104
	v_or_b32_e32 v104, 32, v140
	v_mad_i64_i32 v[116:117], s[24:25], v160, s47, v[118:119]
	v_lshl_add_u64 v[116:117], v[116:117], 0, v[120:121]
	s_waitcnt vmcnt(0)
	v_fmamk_f32 v105, v122, 0x3a800000, v150
	v_rsq_f32_e32 v122, v105
	v_ashrrev_i32_e32 v105, 31, v104
	v_lshl_add_u64 v[124:125], v[104:105], 2, s[4:5]
	v_pk_mul_f32 v[100:101], v[100:101], v[122:123] op_sel_hi:[1,0]
	v_pk_mul_f32 v[114:115], v[114:115], v[122:123] op_sel_hi:[1,0]
	v_pk_mul_f32 v[106:107], v[106:107], v[122:123] op_sel_hi:[1,0]
	v_pk_mul_f32 v[110:111], v[110:111], v[122:123] op_sel_hi:[1,0]
	v_pk_mul_f32 v[108:109], v[108:109], v[122:123] op_sel_hi:[1,0]
	v_pk_mul_f32 v[112:113], v[112:113], v[122:123] op_sel_hi:[1,0]
	v_pk_mul_f32 v[98:99], v[98:99], v[122:123] op_sel_hi:[1,0]
	v_pk_mul_f32 v[102:103], v[102:103], v[122:123] op_sel_hi:[1,0]
	v_mul_f32_e32 v141, 0xbfb8aa3b, v101
	v_mul_f32_e32 v105, 0xbfb8aa3b, v115
	v_mul_f32_e32 v122, 0xbfb8aa3b, v107
	v_mul_f32_e32 v123, 0xbfb8aa3b, v111
	v_mul_f32_e32 v126, 0xbfb8aa3b, v109
	v_mul_f32_e32 v127, 0xbfb8aa3b, v113
	v_mul_f32_e32 v128, 0xbfb8aa3b, v99
	v_mul_f32_e32 v129, 0xbfb8aa3b, v103
	v_exp_f32_e32 v141, v141
	v_exp_f32_e32 v105, v105
	v_exp_f32_e32 v122, v122
	v_exp_f32_e32 v123, v123
	v_exp_f32_e32 v126, v126
	v_exp_f32_e32 v127, v127
	v_exp_f32_e32 v128, v128
	v_exp_f32_e32 v129, v129
	v_add_f32_e32 v141, 1.0, v141
	v_add_f32_e32 v105, 1.0, v105
	v_add_f32_e32 v122, 1.0, v122
	v_add_f32_e32 v123, 1.0, v123
	v_add_f32_e32 v126, 1.0, v126
	v_add_f32_e32 v127, 1.0, v127
	v_add_f32_e32 v128, 1.0, v128
	v_add_f32_e32 v129, 1.0, v129
	v_rcp_f32_e32 v141, v141
	v_rcp_f32_e32 v105, v105
	v_rcp_f32_e32 v122, v122
	v_rcp_f32_e32 v123, v123
	v_rcp_f32_e32 v126, v126
	v_rcp_f32_e32 v127, v127
	v_rcp_f32_e32 v128, v128
	v_rcp_f32_e32 v129, v129
	v_mul_f32_e32 v101, v101, v141
	v_mul_f32_e32 v105, v115, v105
	v_mul_f32_e32 v107, v107, v122
	v_mul_f32_e32 v111, v111, v123
	v_mul_f32_e32 v109, v109, v126
	v_mul_f32_e32 v113, v113, v127
	v_mul_f32_e32 v99, v99, v128
	v_mul_f32_e32 v103, v103, v129
	v_mul_f32_e32 v101, v100, v101
	v_mul_f32_e32 v105, v114, v105
	v_mul_f32_e32 v106, v106, v107
	v_mul_f32_e32 v107, v110, v111
	v_mul_f32_e32 v108, v108, v109
	v_mul_f32_e32 v109, v112, v113
	v_mul_f32_e32 v110, v98, v99
	v_mul_f32_e32 v102, v102, v103
	v_cvt_pk_bf16_f32 v98, v105, v106
	v_cvt_pk_bf16_f32 v99, v107, v108
	v_cvt_pk_bf16_f32 v100, v109, v110
	v_cvt_pk_bf16_f32 v101, v102, v101
	global_store_dwordx4 v[116:117], v[98:101], off sc1
	global_load_dword v102, v[124:125], off
	s_nop 0
	v_mov_b32_e32 v99, v90
	v_mov_b32_e32 v90, v95
	v_mov_b32_e32 v95, v92
	v_mov_b32_e32 v92, v97
	v_mov_b32_e32 v97, v82
	v_mov_b32_e32 v82, v87
	v_mov_b32_e32 v87, v84
	v_mov_b32_e32 v84, v89
	v_mov_b32_e32 v98, v94
	v_mov_b32_e32 v94, v96
	v_mov_b32_e32 v96, v86
	v_mov_b32_e32 v86, v88
	v_or_b32_e32 v88, 48, v140
	v_mad_i64_i32 v[100:101], s[24:25], v104, s47, v[118:119]
	v_lshl_add_u64 v[100:101], v[100:101], 0, v[120:121]
	s_waitcnt vmcnt(0)
; __device__ __forceinline__ unsigned cvt_pk_bf16(float lo, float hi) { unsigned r; asm volatile("v_cvt_pk_bf16_f32 %0, %1, %2" : "=v"(r) : "v"(lo), "v"(hi)); return r; }
; __device__ __forceinline__ float silu_f(float x) { return x * sigmoid_f(x); }
;     __device__ __forceinline__ void operator()(const f32x4 (&acc)[2][2][4][2], const Unit& u, int wr, int wc, int fr, int fq) const {
;         const int row0 = u.pm * BM + wr * 64 + fr, col0 = u.pn * 128 + wc * 32 + 8 * fq;
; #pragma unroll
;         for (int ai = 0; ai < 2; ++ai)
; #pragma unroll
;             for (int m = 0; m < 4; ++m) {
;                 const int row = row0 + ai * HALF + m * 16;
;                 const float r = __builtin_amdgcn_rsqf(rss[row] * (1.f / 1024.f) + NEPS);
;                 float o[8];
; #pragma unroll
;                 for (int n = 0; n < 2; ++n)
; #pragma unroll
;                     for (int e = 0; e < 4; ++e) o[4 * n + e] = silu_f(acc[ai][0][m][n][e] * r) * (acc[ai][1][m][n][e] * r);
;                 u32x4 w; w.x = cvt_pk_bf16(o[0], o[1]); w.y = cvt_pk_bf16(o[2], o[3]); w.z = cvt_pk_bf16(o[4], o[5]); w.w = cvt_pk_bf16(o[6], o[7]);
;                 *(u32x4*)(O + (size_t)row * 2816 + col0) = w;
	v_fmamk_f32 v89, v102, 0x3a800000, v150
	v_rsq_f32_e32 v102, v89
	v_ashrrev_i32_e32 v89, 31, v88
	v_lshl_add_u64 v[104:105], v[88:89], 2, s[4:5]
	v_pk_mul_f32 v[84:85], v[84:85], v[102:103] op_sel_hi:[1,0]
	v_pk_mul_f32 v[98:99], v[98:99], v[102:103] op_sel_hi:[1,0]
	v_pk_mul_f32 v[90:91], v[90:91], v[102:103] op_sel_hi:[1,0]
	v_pk_mul_f32 v[94:95], v[94:95], v[102:103] op_sel_hi:[1,0]
	v_pk_mul_f32 v[92:93], v[92:93], v[102:103] op_sel_hi:[1,0]
	v_pk_mul_f32 v[96:97], v[96:97], v[102:103] op_sel_hi:[1,0]
	v_pk_mul_f32 v[82:83], v[82:83], v[102:103] op_sel_hi:[1,0]
	v_pk_mul_f32 v[86:87], v[86:87], v[102:103] op_sel_hi:[1,0]
	v_mul_f32_e32 v110, 0xbfb8aa3b, v85
	v_mul_f32_e32 v89, 0xbfb8aa3b, v99
	v_mul_f32_e32 v102, 0xbfb8aa3b, v91
	v_mul_f32_e32 v103, 0xbfb8aa3b, v95
	v_mul_f32_e32 v106, 0xbfb8aa3b, v93
	v_mul_f32_e32 v107, 0xbfb8aa3b, v97
	v_mul_f32_e32 v108, 0xbfb8aa3b, v83
	v_mul_f32_e32 v109, 0xbfb8aa3b, v87
	v_exp_f32_e32 v110, v110
	v_exp_f32_e32 v89, v89
	v_exp_f32_e32 v102, v102
	v_exp_f32_e32 v103, v103
	v_exp_f32_e32 v106, v106
	v_exp_f32_e32 v107, v107
	v_exp_f32_e32 v108, v108
	v_exp_f32_e32 v109, v109
	v_add_f32_e32 v110, 1.0, v110
	v_add_f32_e32 v89, 1.0, v89
	v_add_f32_e32 v102, 1.0, v102
	v_add_f32_e32 v103, 1.0, v103
	v_add_f32_e32 v106, 1.0, v106
	v_add_f32_e32 v107, 1.0, v107
	v_add_f32_e32 v108, 1.0, v108
	v_add_f32_e32 v109, 1.0, v109
	v_rcp_f32_e32 v110, v110
	v_rcp_f32_e32 v89, v89
	v_rcp_f32_e32 v102, v102
	v_rcp_f32_e32 v103, v103
	v_rcp_f32_e32 v106, v106
	v_rcp_f32_e32 v107, v107
	v_rcp_f32_e32 v108, v108
	v_rcp_f32_e32 v109, v109
	v_mul_f32_e32 v85, v85, v110
	v_mul_f32_e32 v89, v99, v89
	v_mul_f32_e32 v91, v91, v102
	v_mul_f32_e32 v95, v95, v103
	v_mul_f32_e32 v93, v93, v106
	v_mul_f32_e32 v97, v97, v107
	v_mul_f32_e32 v83, v83, v108
	v_mul_f32_e32 v87, v87, v109
	v_mul_f32_e32 v85, v84, v85
	v_mul_f32_e32 v89, v98, v89
	v_mul_f32_e32 v90, v90, v91
	v_mul_f32_e32 v91, v94, v95
	v_mul_f32_e32 v92, v92, v93
	v_mul_f32_e32 v93, v96, v97
	v_mul_f32_e32 v94, v82, v83
	v_mul_f32_e32 v86, v86, v87
	v_cvt_pk_bf16_f32 v82, v89, v90
	v_cvt_pk_bf16_f32 v83, v91, v92
	v_cvt_pk_bf16_f32 v84, v93, v94
	v_cvt_pk_bf16_f32 v85, v86, v85
	global_store_dwordx4 v[100:101], v[82:85], off sc1
	global_load_dword v84, v[104:105], off
	s_nop 0
	v_mov_b32_e32 v82, v78
	v_mov_b32_e32 v78, v80
	v_mov_b32_e32 v80, v66
	v_mov_b32_e32 v66, v68
	v_mov_b32_e32 v83, v74
	v_mov_b32_e32 v74, v79
	v_mov_b32_e32 v79, v76
	v_mov_b32_e32 v76, v81
	v_mov_b32_e32 v81, v70
	v_mov_b32_e32 v70, v67
	v_mov_b32_e32 v67, v72
	v_mov_b32_e32 v72, v69
	s_waitcnt vmcnt(0)
	v_fmamk_f32 v68, v84, 0x3a800000, v150
	v_rsq_f32_e32 v68, v68
	v_mad_i64_i32 v[84:85], s[24:25], v88, s47, v[118:119]
	v_lshl_add_u64 v[84:85], v[84:85], 0, v[120:121]
	v_pk_mul_f32 v[82:83], v[82:83], v[68:69] op_sel_hi:[1,0]
	v_pk_mul_f32 v[74:75], v[74:75], v[68:69] op_sel_hi:[1,0]
	v_pk_mul_f32 v[78:79], v[78:79], v[68:69] op_sel_hi:[1,0]
	v_pk_mul_f32 v[76:77], v[76:77], v[68:69] op_sel_hi:[1,0]
	v_pk_mul_f32 v[80:81], v[80:81], v[68:69] op_sel_hi:[1,0]
	v_pk_mul_f32 v[70:71], v[70:71], v[68:69] op_sel_hi:[1,0]
	v_pk_mul_f32 v[66:67], v[66:67], v[68:69] op_sel_hi:[1,0]
	v_pk_mul_f32 v[68:69], v[72:73], v[68:69] op_sel_hi:[1,0]
	v_mul_f32_e32 v72, 0xbfb8aa3b, v83
	v_mul_f32_e32 v91, 0xbfb8aa3b, v69
	v_mul_f32_e32 v73, 0xbfb8aa3b, v75
	v_mul_f32_e32 v86, 0xbfb8aa3b, v79
	v_mul_f32_e32 v87, 0xbfb8aa3b, v77
	v_mul_f32_e32 v88, 0xbfb8aa3b, v81
	v_mul_f32_e32 v89, 0xbfb8aa3b, v71
	v_mul_f32_e32 v90, 0xbfb8aa3b, v67
	v_exp_f32_e32 v91, v91
	v_exp_f32_e32 v72, v72
	v_exp_f32_e32 v73, v73
	v_exp_f32_e32 v86, v86
	v_exp_f32_e32 v87, v87
	v_exp_f32_e32 v88, v88
	v_exp_f32_e32 v89, v89
	v_exp_f32_e32 v90, v90
	v_add_f32_e32 v91, 1.0, v91
	v_add_f32_e32 v72, 1.0, v72
	v_add_f32_e32 v73, 1.0, v73
	v_add_f32_e32 v86, 1.0, v86
	v_add_f32_e32 v87, 1.0, v87
	v_add_f32_e32 v88, 1.0, v88
	v_add_f32_e32 v89, 1.0, v89
	v_add_f32_e32 v90, 1.0, v90
	v_rcp_f32_e32 v91, v91
	v_rcp_f32_e32 v72, v72
	v_rcp_f32_e32 v73, v73
	v_rcp_f32_e32 v86, v86
	v_rcp_f32_e32 v87, v87
	v_rcp_f32_e32 v88, v88
	v_rcp_f32_e32 v89, v89
	v_rcp_f32_e32 v90, v90
	v_mul_f32_e32 v69, v69, v91
	v_mul_f32_e32 v72, v83, v72
	v_mul_f32_e32 v73, v75, v73
	v_mul_f32_e32 v75, v79, v86
	v_mul_f32_e32 v77, v77, v87
	v_mul_f32_e32 v79, v81, v88
	v_mul_f32_e32 v71, v71, v89
	v_mul_f32_e32 v67, v67, v90
	v_mul_f32_e32 v69, v68, v69
	v_mul_f32_e32 v72, v82, v72
	v_mul_f32_e32 v73, v74, v73
	v_mul_f32_e32 v74, v78, v75
	v_mul_f32_e32 v75, v76, v77
	v_mul_f32_e32 v76, v80, v79
	v_mul_f32_e32 v70, v70, v71
	v_mul_f32_e32 v71, v66, v67
	v_cvt_pk_bf16_f32 v66, v72, v73
	v_cvt_pk_bf16_f32 v67, v74, v75
	v_cvt_pk_bf16_f32 v68, v76, v70
	v_cvt_pk_bf16_f32 v69, v71, v69
	global_store_dwordx4 v[84:85], v[66:69], off sc1
	global_load_dword v68, v[142:143], off offset:512
	s_nop 0
	v_mov_b32_e32 v66, v62
	v_mov_b32_e32 v62, v64
	v_mov_b32_e32 v64, v50
	v_mov_b32_e32 v50, v52
	v_mov_b32_e32 v67, v58
	v_mov_b32_e32 v58, v63
	v_mov_b32_e32 v63, v60
	v_mov_b32_e32 v60, v65
	v_mov_b32_e32 v65, v54
	v_mov_b32_e32 v54, v51
	v_mov_b32_e32 v51, v56
	v_mov_b32_e32 v56, v53
	v_add_u32_e32 v53, 0x80, v140
	s_waitcnt vmcnt(0)
; __device__ __forceinline__ unsigned cvt_pk_bf16(float lo, float hi) { unsigned r; asm volatile("v_cvt_pk_bf16_f32 %0, %1, %2" : "=v"(r) : "v"(lo), "v"(hi)); return r; }
; __device__ __forceinline__ float silu_f(float x) { return x * sigmoid_f(x); }
;     __device__ __forceinline__ void operator()(const f32x4 (&acc)[2][2][4][2], const Unit& u, int wr, int wc, int fr, int fq) const {
;         const int row0 = u.pm * BM + wr * 64 + fr, col0 = u.pn * 128 + wc * 32 + 8 * fq;
; #pragma unroll
;         for (int ai = 0; ai < 2; ++ai)
; #pragma unroll
;             for (int m = 0; m < 4; ++m) {
;                 const int row = row0 + ai * HALF + m * 16;
;                 const float r = __builtin_amdgcn_rsqf(rss[row] * (1.f / 1024.f) + NEPS);
;                 float o[8];
; #pragma unroll
;                 for (int n = 0; n < 2; ++n)
; #pragma unroll
;                     for (int e = 0; e < 4; ++e) o[4 * n + e] = silu_f(acc[ai][0][m][n][e] * r) * (acc[ai][1][m][n][e] * r);
;                 u32x4 w; w.x = cvt_pk_bf16(o[0], o[1]); w.y = cvt_pk_bf16(o[2], o[3]); w.z = cvt_pk_bf16(o[4], o[5]); w.w = cvt_pk_bf16(o[6], o[7]);
;                 *(u32x4*)(O + (size_t)row * 2816 + col0) = w;
	v_fmamk_f32 v52, v68, 0x3a800000, v150
	v_rsq_f32_e32 v52, v52
	v_mad_i64_i32 v[68:69], s[24:25], v53, s47, v[118:119]
	v_lshl_add_u64 v[68:69], v[68:69], 0, v[120:121]
	v_pk_mul_f32 v[66:67], v[66:67], v[52:53] op_sel_hi:[1,0]
	v_pk_mul_f32 v[58:59], v[58:59], v[52:53] op_sel_hi:[1,0]
	v_pk_mul_f32 v[62:63], v[62:63], v[52:53] op_sel_hi:[1,0]
	v_pk_mul_f32 v[60:61], v[60:61], v[52:53] op_sel_hi:[1,0]
	v_pk_mul_f32 v[64:65], v[64:65], v[52:53] op_sel_hi:[1,0]
	v_pk_mul_f32 v[54:55], v[54:55], v[52:53] op_sel_hi:[1,0]
	v_pk_mul_f32 v[50:51], v[50:51], v[52:53] op_sel_hi:[1,0]
	v_pk_mul_f32 v[52:53], v[56:57], v[52:53] op_sel_hi:[1,0]
	v_mul_f32_e32 v56, 0xbfb8aa3b, v67
	v_mul_f32_e32 v75, 0xbfb8aa3b, v53
	v_mul_f32_e32 v57, 0xbfb8aa3b, v59
	v_mul_f32_e32 v70, 0xbfb8aa3b, v63
	v_mul_f32_e32 v71, 0xbfb8aa3b, v61
	v_mul_f32_e32 v72, 0xbfb8aa3b, v65
	v_mul_f32_e32 v73, 0xbfb8aa3b, v55
	v_mul_f32_e32 v74, 0xbfb8aa3b, v51
	v_exp_f32_e32 v75, v75
	v_exp_f32_e32 v56, v56
	v_exp_f32_e32 v57, v57
	v_exp_f32_e32 v70, v70
	v_exp_f32_e32 v71, v71
	v_exp_f32_e32 v72, v72
	v_exp_f32_e32 v73, v73
	v_exp_f32_e32 v74, v74
	v_add_f32_e32 v75, 1.0, v75
	v_add_f32_e32 v56, 1.0, v56
	v_add_f32_e32 v57, 1.0, v57
	v_add_f32_e32 v70, 1.0, v70
	v_add_f32_e32 v71, 1.0, v71
	v_add_f32_e32 v72, 1.0, v72
	v_add_f32_e32 v73, 1.0, v73
	v_add_f32_e32 v74, 1.0, v74
	v_rcp_f32_e32 v75, v75
	v_rcp_f32_e32 v56, v56
	v_rcp_f32_e32 v57, v57
	v_rcp_f32_e32 v70, v70
	v_rcp_f32_e32 v71, v71
	v_rcp_f32_e32 v72, v72
	v_rcp_f32_e32 v73, v73
	v_rcp_f32_e32 v74, v74
	v_mul_f32_e32 v53, v53, v75
	v_mul_f32_e32 v56, v67, v56
	v_mul_f32_e32 v57, v59, v57
	v_mul_f32_e32 v59, v63, v70
	v_mul_f32_e32 v61, v61, v71
	v_mul_f32_e32 v63, v65, v72
	v_mul_f32_e32 v55, v55, v73
	v_mul_f32_e32 v51, v51, v74
	v_mul_f32_e32 v53, v52, v53
	v_mul_f32_e32 v56, v66, v56
	v_mul_f32_e32 v57, v58, v57
	v_mul_f32_e32 v58, v62, v59
	v_mul_f32_e32 v59, v60, v61
	v_mul_f32_e32 v60, v64, v63
	v_mul_f32_e32 v54, v54, v55
	v_mul_f32_e32 v55, v50, v51
	v_cvt_pk_bf16_f32 v50, v56, v57
	v_cvt_pk_bf16_f32 v51, v58, v59
	v_cvt_pk_bf16_f32 v52, v60, v54
	v_cvt_pk_bf16_f32 v53, v55, v53
	global_store_dwordx4 v[68:69], v[50:53], off sc1
	global_load_dword v52, v[142:143], off offset:576
	s_nop 0
	v_mov_b32_e32 v50, v46
	v_mov_b32_e32 v46, v48
	v_mov_b32_e32 v48, v34
	v_mov_b32_e32 v34, v36
	v_mov_b32_e32 v51, v42
	v_mov_b32_e32 v42, v47
	v_mov_b32_e32 v47, v44
	v_mov_b32_e32 v44, v49
	v_mov_b32_e32 v49, v38
	v_mov_b32_e32 v38, v35
	v_mov_b32_e32 v35, v40
	v_mov_b32_e32 v40, v37
	v_add_u32_e32 v37, 0x90, v140
	s_waitcnt vmcnt(0)
	v_fmamk_f32 v36, v52, 0x3a800000, v150
	v_rsq_f32_e32 v36, v36
	v_mad_i64_i32 v[52:53], s[24:25], v37, s47, v[118:119]
	v_lshl_add_u64 v[52:53], v[52:53], 0, v[120:121]
	v_pk_mul_f32 v[50:51], v[50:51], v[36:37] op_sel_hi:[1,0]
	v_pk_mul_f32 v[42:43], v[42:43], v[36:37] op_sel_hi:[1,0]
	v_pk_mul_f32 v[46:47], v[46:47], v[36:37] op_sel_hi:[1,0]
	v_pk_mul_f32 v[44:45], v[44:45], v[36:37] op_sel_hi:[1,0]
	v_pk_mul_f32 v[48:49], v[48:49], v[36:37] op_sel_hi:[1,0]
	v_pk_mul_f32 v[38:39], v[38:39], v[36:37] op_sel_hi:[1,0]
	v_pk_mul_f32 v[34:35], v[34:35], v[36:37] op_sel_hi:[1,0]
	v_pk_mul_f32 v[36:37], v[40:41], v[36:37] op_sel_hi:[1,0]
	v_mul_f32_e32 v40, 0xbfb8aa3b, v51
	v_mul_f32_e32 v59, 0xbfb8aa3b, v37
	v_mul_f32_e32 v41, 0xbfb8aa3b, v43
	v_mul_f32_e32 v54, 0xbfb8aa3b, v47
	v_mul_f32_e32 v55, 0xbfb8aa3b, v45
	v_mul_f32_e32 v56, 0xbfb8aa3b, v49
	v_mul_f32_e32 v57, 0xbfb8aa3b, v39
	v_mul_f32_e32 v58, 0xbfb8aa3b, v35
	v_exp_f32_e32 v59, v59
	v_exp_f32_e32 v40, v40
	v_exp_f32_e32 v41, v41
	v_exp_f32_e32 v54, v54
	v_exp_f32_e32 v55, v55
	v_exp_f32_e32 v56, v56
	v_exp_f32_e32 v57, v57
	v_exp_f32_e32 v58, v58
	v_add_f32_e32 v59, 1.0, v59
	v_add_f32_e32 v40, 1.0, v40
	v_add_f32_e32 v41, 1.0, v41
	v_add_f32_e32 v54, 1.0, v54
	v_add_f32_e32 v55, 1.0, v55
	v_add_f32_e32 v56, 1.0, v56
	v_add_f32_e32 v57, 1.0, v57
	v_add_f32_e32 v58, 1.0, v58
	v_rcp_f32_e32 v59, v59
	v_rcp_f32_e32 v40, v40
	v_rcp_f32_e32 v41, v41
	v_rcp_f32_e32 v54, v54
	v_rcp_f32_e32 v55, v55
	v_rcp_f32_e32 v56, v56
	v_rcp_f32_e32 v57, v57
	v_rcp_f32_e32 v58, v58
	v_mul_f32_e32 v37, v37, v59
	v_mul_f32_e32 v40, v51, v40
	v_mul_f32_e32 v41, v43, v41
	v_mul_f32_e32 v43, v47, v54
	v_mul_f32_e32 v45, v45, v55
	v_mul_f32_e32 v47, v49, v56
	v_mul_f32_e32 v39, v39, v57
	v_mul_f32_e32 v35, v35, v58
	v_mul_f32_e32 v37, v36, v37
	v_mul_f32_e32 v40, v50, v40
	v_mul_f32_e32 v41, v42, v41
	v_mul_f32_e32 v42, v46, v43
	v_mul_f32_e32 v43, v44, v45
	v_mul_f32_e32 v44, v48, v47
	v_mul_f32_e32 v38, v38, v39
	v_mul_f32_e32 v39, v34, v35
	v_cvt_pk_bf16_f32 v34, v40, v41
	v_cvt_pk_bf16_f32 v35, v42, v43
	v_cvt_pk_bf16_f32 v36, v44, v38
	v_cvt_pk_bf16_f32 v37, v39, v37
	global_store_dwordx4 v[52:53], v[34:37], off sc1
	global_load_dword v36, v[142:143], off offset:640
	s_nop 0
	v_mov_b32_e32 v34, v30
	v_mov_b32_e32 v30, v32
	v_mov_b32_e32 v32, v18
	v_mov_b32_e32 v18, v20
	v_mov_b32_e32 v35, v26
	v_mov_b32_e32 v26, v31
	v_mov_b32_e32 v31, v28
	v_mov_b32_e32 v28, v33
	v_mov_b32_e32 v33, v22
	v_mov_b32_e32 v22, v19
	v_mov_b32_e32 v19, v24
	v_mov_b32_e32 v24, v21
	v_add_u32_e32 v21, 0xa0, v140
	s_waitcnt vmcnt(0)
; __device__ __forceinline__ unsigned cvt_pk_bf16(float lo, float hi) { unsigned r; asm volatile("v_cvt_pk_bf16_f32 %0, %1, %2" : "=v"(r) : "v"(lo), "v"(hi)); return r; }
; __device__ __forceinline__ float silu_f(float x) { return x * sigmoid_f(x); }
;     __device__ __forceinline__ void operator()(const f32x4 (&acc)[2][2][4][2], const Unit& u, int wr, int wc, int fr, int fq) const {
;         const int row0 = u.pm * BM + wr * 64 + fr, col0 = u.pn * 128 + wc * 32 + 8 * fq;
; #pragma unroll
;         for (int ai = 0; ai < 2; ++ai)
; #pragma unroll
;             for (int m = 0; m < 4; ++m) {
;                 const int row = row0 + ai * HALF + m * 16;
;                 const float r = __builtin_amdgcn_rsqf(rss[row] * (1.f / 1024.f) + NEPS);
;                 float o[8];
; #pragma unroll
;                 for (int n = 0; n < 2; ++n)
; #pragma unroll
;                     for (int e = 0; e < 4; ++e) o[4 * n + e] = silu_f(acc[ai][0][m][n][e] * r) * (acc[ai][1][m][n][e] * r);
;                 u32x4 w; w.x = cvt_pk_bf16(o[0], o[1]); w.y = cvt_pk_bf16(o[2], o[3]); w.z = cvt_pk_bf16(o[4], o[5]); w.w = cvt_pk_bf16(o[6], o[7]);
;                 *(u32x4*)(O + (size_t)row * 2816 + col0) = w;
	v_fmamk_f32 v20, v36, 0x3a800000, v150
	v_rsq_f32_e32 v20, v20
	v_mad_i64_i32 v[36:37], s[24:25], v21, s47, v[118:119]
	v_lshl_add_u64 v[36:37], v[36:37], 0, v[120:121]
	v_pk_mul_f32 v[34:35], v[34:35], v[20:21] op_sel_hi:[1,0]
	v_pk_mul_f32 v[26:27], v[26:27], v[20:21] op_sel_hi:[1,0]
	v_pk_mul_f32 v[30:31], v[30:31], v[20:21] op_sel_hi:[1,0]
	v_pk_mul_f32 v[28:29], v[28:29], v[20:21] op_sel_hi:[1,0]
	v_pk_mul_f32 v[32:33], v[32:33], v[20:21] op_sel_hi:[1,0]
	v_pk_mul_f32 v[22:23], v[22:23], v[20:21] op_sel_hi:[1,0]
	v_pk_mul_f32 v[18:19], v[18:19], v[20:21] op_sel_hi:[1,0]
	v_pk_mul_f32 v[20:21], v[24:25], v[20:21] op_sel_hi:[1,0]
	v_mul_f32_e32 v24, 0xbfb8aa3b, v35
	v_mul_f32_e32 v43, 0xbfb8aa3b, v21
	v_mul_f32_e32 v25, 0xbfb8aa3b, v27
	v_mul_f32_e32 v38, 0xbfb8aa3b, v31
	v_mul_f32_e32 v39, 0xbfb8aa3b, v29
	v_mul_f32_e32 v40, 0xbfb8aa3b, v33
	v_mul_f32_e32 v41, 0xbfb8aa3b, v23
	v_mul_f32_e32 v42, 0xbfb8aa3b, v19
	v_exp_f32_e32 v43, v43
	v_exp_f32_e32 v24, v24
	v_exp_f32_e32 v25, v25
	v_exp_f32_e32 v38, v38
	v_exp_f32_e32 v39, v39
	v_exp_f32_e32 v40, v40
	v_exp_f32_e32 v41, v41
	v_exp_f32_e32 v42, v42
	v_add_f32_e32 v43, 1.0, v43
	v_add_f32_e32 v24, 1.0, v24
	v_add_f32_e32 v25, 1.0, v25
	v_add_f32_e32 v38, 1.0, v38
	v_add_f32_e32 v39, 1.0, v39
	v_add_f32_e32 v40, 1.0, v40
	v_add_f32_e32 v41, 1.0, v41
	v_add_f32_e32 v42, 1.0, v42
	v_rcp_f32_e32 v43, v43
	v_rcp_f32_e32 v24, v24
	v_rcp_f32_e32 v25, v25
	v_rcp_f32_e32 v38, v38
	v_rcp_f32_e32 v39, v39
	v_rcp_f32_e32 v40, v40
	v_rcp_f32_e32 v41, v41
	v_rcp_f32_e32 v42, v42
	v_mul_f32_e32 v21, v21, v43
	v_mul_f32_e32 v24, v35, v24
	v_mul_f32_e32 v25, v27, v25
	v_mul_f32_e32 v27, v31, v38
	v_mul_f32_e32 v29, v29, v39
	v_mul_f32_e32 v31, v33, v40
	v_mul_f32_e32 v23, v23, v41
	v_mul_f32_e32 v19, v19, v42
	v_mul_f32_e32 v21, v20, v21
	v_mul_f32_e32 v24, v34, v24
	v_mul_f32_e32 v25, v26, v25
	v_mul_f32_e32 v26, v30, v27
	v_mul_f32_e32 v27, v28, v29
	v_mul_f32_e32 v28, v32, v31
	v_mul_f32_e32 v22, v22, v23
	v_mul_f32_e32 v23, v18, v19
	v_cvt_pk_bf16_f32 v18, v24, v25
	v_cvt_pk_bf16_f32 v19, v26, v27
	v_cvt_pk_bf16_f32 v20, v28, v22
	v_cvt_pk_bf16_f32 v21, v23, v21
	global_store_dwordx4 v[36:37], v[18:21], off sc1
	global_load_dword v20, v[142:143], off offset:704
	s_nop 0
	v_mov_b32_e32 v18, v14
	v_mov_b32_e32 v14, v16
	v_mov_b32_e32 v16, v2
	v_mov_b32_e32 v2, v4
	v_mov_b32_e32 v19, v10
	v_mov_b32_e32 v10, v15
	v_mov_b32_e32 v15, v12
	v_mov_b32_e32 v12, v17
	v_mov_b32_e32 v17, v6
	v_mov_b32_e32 v6, v3
	v_mov_b32_e32 v3, v8
	v_mov_b32_e32 v8, v5
	v_add_u32_e32 v5, 0xb0, v140
	s_waitcnt vmcnt(0)
	v_fmamk_f32 v4, v20, 0x3a800000, v150
	v_rsq_f32_e32 v4, v4
	v_mad_i64_i32 v[20:21], s[24:25], v5, s47, v[118:119]
	v_lshl_add_u64 v[20:21], v[20:21], 0, v[120:121]
	v_pk_mul_f32 v[18:19], v[18:19], v[4:5] op_sel_hi:[1,0]
	v_pk_mul_f32 v[10:11], v[10:11], v[4:5] op_sel_hi:[1,0]
	v_pk_mul_f32 v[14:15], v[14:15], v[4:5] op_sel_hi:[1,0]
	v_pk_mul_f32 v[12:13], v[12:13], v[4:5] op_sel_hi:[1,0]
	v_pk_mul_f32 v[16:17], v[16:17], v[4:5] op_sel_hi:[1,0]
	v_pk_mul_f32 v[6:7], v[6:7], v[4:5] op_sel_hi:[1,0]
	v_pk_mul_f32 v[2:3], v[2:3], v[4:5] op_sel_hi:[1,0]
	v_pk_mul_f32 v[4:5], v[8:9], v[4:5] op_sel_hi:[1,0]
	v_mul_f32_e32 v8, 0xbfb8aa3b, v19
	v_mul_f32_e32 v27, 0xbfb8aa3b, v5
	v_mul_f32_e32 v9, 0xbfb8aa3b, v11
	v_mul_f32_e32 v22, 0xbfb8aa3b, v15
	v_mul_f32_e32 v23, 0xbfb8aa3b, v13
	v_mul_f32_e32 v24, 0xbfb8aa3b, v17
	v_mul_f32_e32 v25, 0xbfb8aa3b, v7
	v_mul_f32_e32 v26, 0xbfb8aa3b, v3
	v_exp_f32_e32 v27, v27
	v_exp_f32_e32 v8, v8
	v_exp_f32_e32 v9, v9
	v_exp_f32_e32 v22, v22
	v_exp_f32_e32 v23, v23
	v_exp_f32_e32 v24, v24
	v_exp_f32_e32 v25, v25
	v_exp_f32_e32 v26, v26
	v_add_f32_e32 v27, 1.0, v27
	v_add_f32_e32 v8, 1.0, v8
	v_add_f32_e32 v9, 1.0, v9
	v_add_f32_e32 v22, 1.0, v22
	v_add_f32_e32 v23, 1.0, v23
	v_add_f32_e32 v24, 1.0, v24
	v_add_f32_e32 v25, 1.0, v25
	v_add_f32_e32 v26, 1.0, v26
	v_rcp_f32_e32 v27, v27
	v_rcp_f32_e32 v8, v8
	v_rcp_f32_e32 v9, v9
	v_rcp_f32_e32 v22, v22
	v_rcp_f32_e32 v23, v23
	v_rcp_f32_e32 v24, v24
	v_rcp_f32_e32 v25, v25
	v_rcp_f32_e32 v26, v26
	v_mul_f32_e32 v5, v5, v27
	v_mul_f32_e32 v8, v19, v8
	v_mul_f32_e32 v9, v11, v9
	v_mul_f32_e32 v11, v15, v22
	v_mul_f32_e32 v13, v13, v23
	v_mul_f32_e32 v15, v17, v24
	v_mul_f32_e32 v7, v7, v25
	v_mul_f32_e32 v3, v3, v26
	v_mul_f32_e32 v5, v4, v5
	v_mul_f32_e32 v8, v18, v8
	v_mul_f32_e32 v9, v10, v9
	v_mul_f32_e32 v10, v14, v11
	v_mul_f32_e32 v11, v12, v13
	v_mul_f32_e32 v12, v16, v15
	v_mul_f32_e32 v6, v6, v7
	v_mul_f32_e32 v7, v2, v3
	v_cvt_pk_bf16_f32 v2, v8, v9
	v_cvt_pk_bf16_f32 v3, v10, v11
	v_cvt_pk_bf16_f32 v4, v12, v6
	v_cvt_pk_bf16_f32 v5, v7, v5
	global_store_dwordx4 v[20:21], v[2:5], off sc1
	s_cbranch_vccnz .LBB0_127
	s_andn2_b64 vcc, exec, s[10:11]
	s_cbranch_vccnz .LBB0_126
	s_barrier
	s_branch .LBB0_126

; __device__ __forceinline__ unsigned cvt_pk_bf16(float lo, float hi) { unsigned r; asm volatile("v_cvt_pk_bf16_f32 %0, %1, %2" : "=v"(r) : "v"(lo), "v"(hi)); return r; }
; __device__ __forceinline__ float silu_f(float x) { return x * sigmoid_f(x); }
;     __device__ __forceinline__ void operator()(const f32x4 (&acc)[2][2][4][2], const Unit& u, int wr, int wc, int fr, int fq) const {
;         const int row0 = u.pm * BM + wr * 64 + fr, col0 = u.pn * 128 + wc * 32 + 8 * fq;
; #pragma unroll
;         for (int ai = 0; ai < 2; ++ai)
; #pragma unroll
;             for (int m = 0; m < 4; ++m) {
;                 const int row = row0 + ai * HALF + m * 16;
;                 const float r = __builtin_amdgcn_rsqf(rss[row] * (1.f / 1024.f) + NEPS);
;                 float o[8];
; #pragma unroll
;                 for (int n = 0; n < 2; ++n)
; #pragma unroll
;                     for (int e = 0; e < 4; ++e) o[4 * n + e] = silu_f(acc[ai][0][m][n][e] * r) * (acc[ai][1][m][n][e] * r);
;                 u32x4 w; w.x = cvt_pk_bf16(o[0], o[1]); w.y = cvt_pk_bf16(o[2], o[3]); w.z = cvt_pk_bf16(o[4], o[5]); w.w = cvt_pk_bf16(o[6], o[7]);
;                 *(u32x4*)(O + (size_t)row * 2816 + col0) = w;
.LBB0_149:
	v_lshl_add_u32 v130, s23, 8, v139
	v_ashrrev_i32_e32 v131, 31, v130
	v_lshl_add_u64 v[132:133], v[130:131], 2, s[4:5]
	global_load_dword v141, v[132:133], off
	v_mov_b32_e32 v131, 0x358637bd
	v_mov_b32_e32 v137, v116
	v_mov_b32_e32 v116, v125
	v_mov_b32_e32 v134, v126
	v_mov_b32_e32 v135, v118
	v_mov_b32_e32 v118, v127
	v_mov_b32_e32 v126, v128
	v_mov_b32_e32 v127, v120
	v_mov_b32_e32 v120, v129
	v_mov_b32_e32 v128, v122
	v_mov_b32_e32 v129, v114
	v_mov_b32_e32 v114, v123
	v_mov_b32_e32 v136, v124
	v_or_b32_e32 v140, 16, v130
	v_lshl_or_b32 v138, s22, 7, v138
	s_movk_i32 s6, 0x1600
	v_mov_b64_e32 v[124:125], s[60:61]
	v_or_b32_e32 v122, s21, v138
	v_mov_b32_e32 v123, 0
	v_mad_i64_i32 v[138:139], s[8:9], v130, s6, v[124:125]
	v_lshlrev_b32_e32 v122, 1, v122
	v_lshl_add_u64 v[138:139], v[138:139], 0, v[122:123]
	s_waitcnt vmcnt(0)
	v_fmamk_f32 v141, v141, 0x3a800000, v131
	v_rsq_f32_e32 v142, v141
	v_ashrrev_i32_e32 v141, 31, v140
	v_lshl_add_u64 v[144:145], v[140:141], 2, s[4:5]
	v_pk_mul_f32 v[116:117], v[116:117], v[142:143] op_sel_hi:[1,0]
	v_pk_mul_f32 v[134:135], v[134:135], v[142:143] op_sel_hi:[1,0]
	v_pk_mul_f32 v[118:119], v[118:119], v[142:143] op_sel_hi:[1,0]
	v_pk_mul_f32 v[126:127], v[126:127], v[142:143] op_sel_hi:[1,0]
	v_pk_mul_f32 v[120:121], v[120:121], v[142:143] op_sel_hi:[1,0]
	v_pk_mul_f32 v[128:129], v[128:129], v[142:143] op_sel_hi:[1,0]
	v_pk_mul_f32 v[114:115], v[114:115], v[142:143] op_sel_hi:[1,0]
	v_pk_mul_f32 v[136:137], v[136:137], v[142:143] op_sel_hi:[1,0]
	v_mul_f32_e32 v150, 0xbfb8aa3b, v117
	v_mul_f32_e32 v141, 0xbfb8aa3b, v135
	v_mul_f32_e32 v142, 0xbfb8aa3b, v119
	v_mul_f32_e32 v143, 0xbfb8aa3b, v127
	v_mul_f32_e32 v146, 0xbfb8aa3b, v121
	v_mul_f32_e32 v147, 0xbfb8aa3b, v129
	v_mul_f32_e32 v148, 0xbfb8aa3b, v115
	v_mul_f32_e32 v149, 0xbfb8aa3b, v137
	v_exp_f32_e32 v150, v150
	v_exp_f32_e32 v141, v141
	v_exp_f32_e32 v142, v142
	v_exp_f32_e32 v143, v143
	v_exp_f32_e32 v146, v146
	v_exp_f32_e32 v147, v147
	v_exp_f32_e32 v148, v148
	v_exp_f32_e32 v149, v149
	v_add_f32_e32 v150, 1.0, v150
	v_add_f32_e32 v141, 1.0, v141
	v_add_f32_e32 v142, 1.0, v142
	v_add_f32_e32 v143, 1.0, v143
	v_add_f32_e32 v146, 1.0, v146
	v_add_f32_e32 v147, 1.0, v147
	v_add_f32_e32 v148, 1.0, v148
	v_add_f32_e32 v149, 1.0, v149
	v_rcp_f32_e32 v150, v150
	v_rcp_f32_e32 v141, v141
	v_rcp_f32_e32 v142, v142
	v_rcp_f32_e32 v143, v143
	v_rcp_f32_e32 v146, v146
	v_rcp_f32_e32 v147, v147
	v_rcp_f32_e32 v148, v148
	v_rcp_f32_e32 v149, v149
	v_mul_f32_e32 v117, v117, v150
	v_mul_f32_e32 v135, v135, v141
	v_mul_f32_e32 v119, v119, v142
	v_mul_f32_e32 v127, v127, v143
	v_mul_f32_e32 v121, v121, v146
	v_mul_f32_e32 v129, v129, v147
	v_mul_f32_e32 v115, v115, v148
	v_mul_f32_e32 v137, v137, v149
	v_mul_f32_e32 v117, v116, v117
	v_mul_f32_e32 v134, v134, v135
	v_mul_f32_e32 v118, v118, v119
	v_mul_f32_e32 v119, v126, v127
	v_mul_f32_e32 v120, v120, v121
	v_mul_f32_e32 v121, v128, v129
	v_mul_f32_e32 v126, v114, v115
	v_mul_f32_e32 v127, v136, v137
	v_cvt_pk_bf16_f32 v114, v134, v118
	v_cvt_pk_bf16_f32 v115, v119, v120
	v_cvt_pk_bf16_f32 v116, v121, v126
	v_cvt_pk_bf16_f32 v117, v127, v117
	global_store_dwordx4 v[138:139], v[114:117], off sc1
	global_load_dword v118, v[144:145], off
	s_nop 0
	v_mov_b32_e32 v115, v106
	v_mov_b32_e32 v106, v111
	v_mov_b32_e32 v111, v108
	v_mov_b32_e32 v108, v113
	v_mov_b32_e32 v113, v98
	v_mov_b32_e32 v98, v103
	v_mov_b32_e32 v103, v100
	v_mov_b32_e32 v100, v105
	v_mov_b32_e32 v114, v110
	v_mov_b32_e32 v110, v112
	v_mov_b32_e32 v112, v102
	v_mov_b32_e32 v102, v104
	v_or_b32_e32 v104, 32, v130
	v_mad_i64_i32 v[116:117], s[8:9], v140, s6, v[124:125]
	v_lshl_add_u64 v[116:117], v[116:117], 0, v[122:123]
	s_waitcnt vmcnt(0)
	v_fmamk_f32 v105, v118, 0x3a800000, v131
	v_rsq_f32_e32 v118, v105
	v_ashrrev_i32_e32 v105, 31, v104
	v_lshl_add_u64 v[120:121], v[104:105], 2, s[4:5]
	v_pk_mul_f32 v[100:101], v[100:101], v[118:119] op_sel_hi:[1,0]
	v_pk_mul_f32 v[114:115], v[114:115], v[118:119] op_sel_hi:[1,0]
	v_pk_mul_f32 v[106:107], v[106:107], v[118:119] op_sel_hi:[1,0]
	v_pk_mul_f32 v[110:111], v[110:111], v[118:119] op_sel_hi:[1,0]
	v_pk_mul_f32 v[108:109], v[108:109], v[118:119] op_sel_hi:[1,0]
	v_pk_mul_f32 v[112:113], v[112:113], v[118:119] op_sel_hi:[1,0]
	v_pk_mul_f32 v[98:99], v[98:99], v[118:119] op_sel_hi:[1,0]
	v_pk_mul_f32 v[102:103], v[102:103], v[118:119] op_sel_hi:[1,0]
	v_mul_f32_e32 v134, 0xbfb8aa3b, v101
	v_mul_f32_e32 v105, 0xbfb8aa3b, v115
	v_mul_f32_e32 v118, 0xbfb8aa3b, v107
	v_mul_f32_e32 v119, 0xbfb8aa3b, v111
	v_mul_f32_e32 v126, 0xbfb8aa3b, v109
	v_mul_f32_e32 v127, 0xbfb8aa3b, v113
	v_mul_f32_e32 v128, 0xbfb8aa3b, v99
	v_mul_f32_e32 v129, 0xbfb8aa3b, v103
	v_exp_f32_e32 v134, v134
	v_exp_f32_e32 v105, v105
	v_exp_f32_e32 v118, v118
	v_exp_f32_e32 v119, v119
	v_exp_f32_e32 v126, v126
	v_exp_f32_e32 v127, v127
	v_exp_f32_e32 v128, v128
	v_exp_f32_e32 v129, v129
	v_add_f32_e32 v134, 1.0, v134
	v_add_f32_e32 v105, 1.0, v105
	v_add_f32_e32 v118, 1.0, v118
	v_add_f32_e32 v119, 1.0, v119
	v_add_f32_e32 v126, 1.0, v126
	v_add_f32_e32 v127, 1.0, v127
	v_add_f32_e32 v128, 1.0, v128
	v_add_f32_e32 v129, 1.0, v129
	v_rcp_f32_e32 v134, v134
	v_rcp_f32_e32 v105, v105
	v_rcp_f32_e32 v118, v118
	v_rcp_f32_e32 v119, v119
	v_rcp_f32_e32 v126, v126
	v_rcp_f32_e32 v127, v127
	v_rcp_f32_e32 v128, v128
	v_rcp_f32_e32 v129, v129
	v_mul_f32_e32 v101, v101, v134
	v_mul_f32_e32 v105, v115, v105
	v_mul_f32_e32 v107, v107, v118
	v_mul_f32_e32 v111, v111, v119
	v_mul_f32_e32 v109, v109, v126
	v_mul_f32_e32 v113, v113, v127
	v_mul_f32_e32 v99, v99, v128
	v_mul_f32_e32 v103, v103, v129
	v_mul_f32_e32 v101, v100, v101
	v_mul_f32_e32 v105, v114, v105
	v_mul_f32_e32 v106, v106, v107
	v_mul_f32_e32 v107, v110, v111
	v_mul_f32_e32 v108, v108, v109
	v_mul_f32_e32 v109, v112, v113
	v_mul_f32_e32 v110, v98, v99
	v_mul_f32_e32 v102, v102, v103
	v_cvt_pk_bf16_f32 v98, v105, v106
	v_cvt_pk_bf16_f32 v99, v107, v108
	v_cvt_pk_bf16_f32 v100, v109, v110
	v_cvt_pk_bf16_f32 v101, v102, v101
	global_store_dwordx4 v[116:117], v[98:101], off sc1
	global_load_dword v102, v[120:121], off
	s_nop 0
	v_mov_b32_e32 v99, v90
	v_mov_b32_e32 v90, v95
	v_mov_b32_e32 v95, v92
	v_mov_b32_e32 v92, v97
	v_mov_b32_e32 v97, v82
	v_mov_b32_e32 v82, v87
	v_mov_b32_e32 v87, v84
	v_mov_b32_e32 v84, v89
	v_mov_b32_e32 v98, v94
	v_mov_b32_e32 v94, v96
	v_mov_b32_e32 v96, v86
	v_mov_b32_e32 v86, v88
	v_or_b32_e32 v88, 48, v130
	v_mad_i64_i32 v[100:101], s[8:9], v104, s6, v[124:125]
	v_lshl_add_u64 v[100:101], v[100:101], 0, v[122:123]
	s_waitcnt vmcnt(0)
; __device__ __forceinline__ unsigned cvt_pk_bf16(float lo, float hi) { unsigned r; asm volatile("v_cvt_pk_bf16_f32 %0, %1, %2" : "=v"(r) : "v"(lo), "v"(hi)); return r; }
; __device__ __forceinline__ float silu_f(float x) { return x * sigmoid_f(x); }
;     __device__ __forceinline__ void operator()(const f32x4 (&acc)[2][2][4][2], const Unit& u, int wr, int wc, int fr, int fq) const {
;         const int row0 = u.pm * BM + wr * 64 + fr, col0 = u.pn * 128 + wc * 32 + 8 * fq;
; #pragma unroll
;         for (int ai = 0; ai < 2; ++ai)
; #pragma unroll
;             for (int m = 0; m < 4; ++m) {
;                 const int row = row0 + ai * HALF + m * 16;
;                 const float r = __builtin_amdgcn_rsqf(rss[row] * (1.f / 1024.f) + NEPS);
;                 float o[8];
; #pragma unroll
;                 for (int n = 0; n < 2; ++n)
; #pragma unroll
;                     for (int e = 0; e < 4; ++e) o[4 * n + e] = silu_f(acc[ai][0][m][n][e] * r) * (acc[ai][1][m][n][e] * r);
;                 u32x4 w; w.x = cvt_pk_bf16(o[0], o[1]); w.y = cvt_pk_bf16(o[2], o[3]); w.z = cvt_pk_bf16(o[4], o[5]); w.w = cvt_pk_bf16(o[6], o[7]);
;                 *(u32x4*)(O + (size_t)row * 2816 + col0) = w;
	v_fmamk_f32 v89, v102, 0x3a800000, v131
	v_rsq_f32_e32 v102, v89
	v_ashrrev_i32_e32 v89, 31, v88
	v_lshl_add_u64 v[104:105], v[88:89], 2, s[4:5]
	v_pk_mul_f32 v[84:85], v[84:85], v[102:103] op_sel_hi:[1,0]
	v_pk_mul_f32 v[98:99], v[98:99], v[102:103] op_sel_hi:[1,0]
	v_pk_mul_f32 v[90:91], v[90:91], v[102:103] op_sel_hi:[1,0]
	v_pk_mul_f32 v[94:95], v[94:95], v[102:103] op_sel_hi:[1,0]
	v_pk_mul_f32 v[92:93], v[92:93], v[102:103] op_sel_hi:[1,0]
	v_pk_mul_f32 v[96:97], v[96:97], v[102:103] op_sel_hi:[1,0]
	v_pk_mul_f32 v[82:83], v[82:83], v[102:103] op_sel_hi:[1,0]
	v_pk_mul_f32 v[86:87], v[86:87], v[102:103] op_sel_hi:[1,0]
	v_mul_f32_e32 v110, 0xbfb8aa3b, v85
	v_mul_f32_e32 v89, 0xbfb8aa3b, v99
	v_mul_f32_e32 v102, 0xbfb8aa3b, v91
	v_mul_f32_e32 v103, 0xbfb8aa3b, v95
	v_mul_f32_e32 v106, 0xbfb8aa3b, v93
	v_mul_f32_e32 v107, 0xbfb8aa3b, v97
	v_mul_f32_e32 v108, 0xbfb8aa3b, v83
	v_mul_f32_e32 v109, 0xbfb8aa3b, v87
	v_exp_f32_e32 v110, v110
	v_exp_f32_e32 v89, v89
	v_exp_f32_e32 v102, v102
	v_exp_f32_e32 v103, v103
	v_exp_f32_e32 v106, v106
	v_exp_f32_e32 v107, v107
	v_exp_f32_e32 v108, v108
	v_exp_f32_e32 v109, v109
	v_add_f32_e32 v110, 1.0, v110
	v_add_f32_e32 v89, 1.0, v89
	v_add_f32_e32 v102, 1.0, v102
	v_add_f32_e32 v103, 1.0, v103
	v_add_f32_e32 v106, 1.0, v106
	v_add_f32_e32 v107, 1.0, v107
	v_add_f32_e32 v108, 1.0, v108
	v_add_f32_e32 v109, 1.0, v109
	v_rcp_f32_e32 v110, v110
	v_rcp_f32_e32 v89, v89
	v_rcp_f32_e32 v102, v102
	v_rcp_f32_e32 v103, v103
	v_rcp_f32_e32 v106, v106
	v_rcp_f32_e32 v107, v107
	v_rcp_f32_e32 v108, v108
	v_rcp_f32_e32 v109, v109
	v_mul_f32_e32 v85, v85, v110
	v_mul_f32_e32 v89, v99, v89
	v_mul_f32_e32 v91, v91, v102
	v_mul_f32_e32 v95, v95, v103
	v_mul_f32_e32 v93, v93, v106
	v_mul_f32_e32 v97, v97, v107
	v_mul_f32_e32 v83, v83, v108
	v_mul_f32_e32 v87, v87, v109
	v_mul_f32_e32 v85, v84, v85
	v_mul_f32_e32 v89, v98, v89
	v_mul_f32_e32 v90, v90, v91
	v_mul_f32_e32 v91, v94, v95
	v_mul_f32_e32 v92, v92, v93
	v_mul_f32_e32 v93, v96, v97
	v_mul_f32_e32 v94, v82, v83
	v_mul_f32_e32 v86, v86, v87
	v_cvt_pk_bf16_f32 v82, v89, v90
	v_cvt_pk_bf16_f32 v83, v91, v92
	v_cvt_pk_bf16_f32 v84, v93, v94
	v_cvt_pk_bf16_f32 v85, v86, v85
	global_store_dwordx4 v[100:101], v[82:85], off sc1
	global_load_dword v84, v[104:105], off
	s_nop 0
	v_mov_b32_e32 v82, v78
	v_mov_b32_e32 v78, v80
	v_mov_b32_e32 v80, v66
	v_mov_b32_e32 v66, v68
	v_mov_b32_e32 v83, v74
	v_mov_b32_e32 v74, v79
	v_mov_b32_e32 v79, v76
	v_mov_b32_e32 v76, v81
	v_mov_b32_e32 v81, v70
	v_mov_b32_e32 v70, v67
	v_mov_b32_e32 v67, v72
	v_mov_b32_e32 v72, v69
	s_waitcnt vmcnt(0)
	v_fmamk_f32 v68, v84, 0x3a800000, v131
	v_rsq_f32_e32 v68, v68
	v_mad_i64_i32 v[84:85], s[4:5], v88, s6, v[124:125]
	v_lshl_add_u64 v[84:85], v[84:85], 0, v[122:123]
	v_pk_mul_f32 v[82:83], v[82:83], v[68:69] op_sel_hi:[1,0]
	v_pk_mul_f32 v[74:75], v[74:75], v[68:69] op_sel_hi:[1,0]
	v_pk_mul_f32 v[78:79], v[78:79], v[68:69] op_sel_hi:[1,0]
	v_pk_mul_f32 v[76:77], v[76:77], v[68:69] op_sel_hi:[1,0]
	v_pk_mul_f32 v[80:81], v[80:81], v[68:69] op_sel_hi:[1,0]
	v_pk_mul_f32 v[70:71], v[70:71], v[68:69] op_sel_hi:[1,0]
	v_pk_mul_f32 v[66:67], v[66:67], v[68:69] op_sel_hi:[1,0]
	v_pk_mul_f32 v[68:69], v[72:73], v[68:69] op_sel_hi:[1,0]
	v_mul_f32_e32 v72, 0xbfb8aa3b, v83
	v_mul_f32_e32 v91, 0xbfb8aa3b, v69
	v_mul_f32_e32 v73, 0xbfb8aa3b, v75
	v_mul_f32_e32 v86, 0xbfb8aa3b, v79
	v_mul_f32_e32 v87, 0xbfb8aa3b, v77
	v_mul_f32_e32 v88, 0xbfb8aa3b, v81
	v_mul_f32_e32 v89, 0xbfb8aa3b, v71
	v_mul_f32_e32 v90, 0xbfb8aa3b, v67
	v_exp_f32_e32 v91, v91
	v_exp_f32_e32 v72, v72
	v_exp_f32_e32 v73, v73
	v_exp_f32_e32 v86, v86
	v_exp_f32_e32 v87, v87
	v_exp_f32_e32 v88, v88
	v_exp_f32_e32 v89, v89
	v_exp_f32_e32 v90, v90
	v_add_f32_e32 v91, 1.0, v91
	v_add_f32_e32 v72, 1.0, v72
	v_add_f32_e32 v73, 1.0, v73
	v_add_f32_e32 v86, 1.0, v86
	v_add_f32_e32 v87, 1.0, v87
	v_add_f32_e32 v88, 1.0, v88
	v_add_f32_e32 v89, 1.0, v89
	v_add_f32_e32 v90, 1.0, v90
	v_rcp_f32_e32 v91, v91
	v_rcp_f32_e32 v72, v72
	v_rcp_f32_e32 v73, v73
	v_rcp_f32_e32 v86, v86
	v_rcp_f32_e32 v87, v87
	v_rcp_f32_e32 v88, v88
	v_rcp_f32_e32 v89, v89
	v_rcp_f32_e32 v90, v90
	v_mul_f32_e32 v69, v69, v91
	v_mul_f32_e32 v72, v83, v72
	v_mul_f32_e32 v73, v75, v73
	v_mul_f32_e32 v75, v79, v86
	v_mul_f32_e32 v77, v77, v87
	v_mul_f32_e32 v79, v81, v88
	v_mul_f32_e32 v71, v71, v89
	v_mul_f32_e32 v67, v67, v90
	v_mul_f32_e32 v69, v68, v69
	v_mul_f32_e32 v72, v82, v72
	v_mul_f32_e32 v73, v74, v73
	v_mul_f32_e32 v74, v78, v75
	v_mul_f32_e32 v75, v76, v77
	v_mul_f32_e32 v76, v80, v79
	v_mul_f32_e32 v70, v70, v71
	v_mul_f32_e32 v71, v66, v67
	v_cvt_pk_bf16_f32 v66, v72, v73
	v_cvt_pk_bf16_f32 v67, v74, v75
	v_cvt_pk_bf16_f32 v68, v76, v70
	v_cvt_pk_bf16_f32 v69, v71, v69
	global_store_dwordx4 v[84:85], v[66:69], off sc1
	global_load_dword v68, v[132:133], off offset:512
	s_nop 0
	v_mov_b32_e32 v66, v62
	v_mov_b32_e32 v62, v64
	v_mov_b32_e32 v64, v50
	v_mov_b32_e32 v50, v52
	v_mov_b32_e32 v67, v58
	v_mov_b32_e32 v58, v63
	v_mov_b32_e32 v63, v60
	v_mov_b32_e32 v60, v65
	v_mov_b32_e32 v65, v54
	v_mov_b32_e32 v54, v51
	v_mov_b32_e32 v51, v56
	v_mov_b32_e32 v56, v53
	v_add_u32_e32 v53, 0x80, v130
	s_waitcnt vmcnt(0)
; __device__ __forceinline__ unsigned cvt_pk_bf16(float lo, float hi) { unsigned r; asm volatile("v_cvt_pk_bf16_f32 %0, %1, %2" : "=v"(r) : "v"(lo), "v"(hi)); return r; }
; __device__ __forceinline__ float silu_f(float x) { return x * sigmoid_f(x); }
;     __device__ __forceinline__ void operator()(const f32x4 (&acc)[2][2][4][2], const Unit& u, int wr, int wc, int fr, int fq) const {
;         const int row0 = u.pm * BM + wr * 64 + fr, col0 = u.pn * 128 + wc * 32 + 8 * fq;
; #pragma unroll
;         for (int ai = 0; ai < 2; ++ai)
; #pragma unroll
;             for (int m = 0; m < 4; ++m) {
;                 const int row = row0 + ai * HALF + m * 16;
;                 const float r = __builtin_amdgcn_rsqf(rss[row] * (1.f / 1024.f) + NEPS);
;                 float o[8];
; #pragma unroll
;                 for (int n = 0; n < 2; ++n)
; #pragma unroll
;                     for (int e = 0; e < 4; ++e) o[4 * n + e] = silu_f(acc[ai][0][m][n][e] * r) * (acc[ai][1][m][n][e] * r);
;                 u32x4 w; w.x = cvt_pk_bf16(o[0], o[1]); w.y = cvt_pk_bf16(o[2], o[3]); w.z = cvt_pk_bf16(o[4], o[5]); w.w = cvt_pk_bf16(o[6], o[7]);
;                 *(u32x4*)(O + (size_t)row * 2816 + col0) = w;
	v_fmamk_f32 v52, v68, 0x3a800000, v131
	v_rsq_f32_e32 v52, v52
	v_mad_i64_i32 v[68:69], s[4:5], v53, s6, v[124:125]
	v_lshl_add_u64 v[68:69], v[68:69], 0, v[122:123]
	v_pk_mul_f32 v[66:67], v[66:67], v[52:53] op_sel_hi:[1,0]
	v_pk_mul_f32 v[58:59], v[58:59], v[52:53] op_sel_hi:[1,0]
	v_pk_mul_f32 v[62:63], v[62:63], v[52:53] op_sel_hi:[1,0]
	v_pk_mul_f32 v[60:61], v[60:61], v[52:53] op_sel_hi:[1,0]
	v_pk_mul_f32 v[64:65], v[64:65], v[52:53] op_sel_hi:[1,0]
	v_pk_mul_f32 v[54:55], v[54:55], v[52:53] op_sel_hi:[1,0]
	v_pk_mul_f32 v[50:51], v[50:51], v[52:53] op_sel_hi:[1,0]
	v_pk_mul_f32 v[52:53], v[56:57], v[52:53] op_sel_hi:[1,0]
	v_mul_f32_e32 v56, 0xbfb8aa3b, v67
	v_mul_f32_e32 v75, 0xbfb8aa3b, v53
	v_mul_f32_e32 v57, 0xbfb8aa3b, v59
	v_mul_f32_e32 v70, 0xbfb8aa3b, v63
	v_mul_f32_e32 v71, 0xbfb8aa3b, v61
	v_mul_f32_e32 v72, 0xbfb8aa3b, v65
	v_mul_f32_e32 v73, 0xbfb8aa3b, v55
	v_mul_f32_e32 v74, 0xbfb8aa3b, v51
	v_exp_f32_e32 v75, v75
	v_exp_f32_e32 v56, v56
	v_exp_f32_e32 v57, v57
	v_exp_f32_e32 v70, v70
	v_exp_f32_e32 v71, v71
	v_exp_f32_e32 v72, v72
	v_exp_f32_e32 v73, v73
	v_exp_f32_e32 v74, v74
	v_add_f32_e32 v75, 1.0, v75
	v_add_f32_e32 v56, 1.0, v56
	v_add_f32_e32 v57, 1.0, v57
	v_add_f32_e32 v70, 1.0, v70
	v_add_f32_e32 v71, 1.0, v71
	v_add_f32_e32 v72, 1.0, v72
	v_add_f32_e32 v73, 1.0, v73
	v_add_f32_e32 v74, 1.0, v74
	v_rcp_f32_e32 v75, v75
	v_rcp_f32_e32 v56, v56
	v_rcp_f32_e32 v57, v57
	v_rcp_f32_e32 v70, v70
	v_rcp_f32_e32 v71, v71
	v_rcp_f32_e32 v72, v72
	v_rcp_f32_e32 v73, v73
	v_rcp_f32_e32 v74, v74
	v_mul_f32_e32 v53, v53, v75
	v_mul_f32_e32 v56, v67, v56
	v_mul_f32_e32 v57, v59, v57
	v_mul_f32_e32 v59, v63, v70
	v_mul_f32_e32 v61, v61, v71
	v_mul_f32_e32 v63, v65, v72
	v_mul_f32_e32 v55, v55, v73
	v_mul_f32_e32 v51, v51, v74
	v_mul_f32_e32 v53, v52, v53
	v_mul_f32_e32 v56, v66, v56
	v_mul_f32_e32 v57, v58, v57
	v_mul_f32_e32 v58, v62, v59
	v_mul_f32_e32 v59, v60, v61
	v_mul_f32_e32 v60, v64, v63
	v_mul_f32_e32 v54, v54, v55
	v_mul_f32_e32 v55, v50, v51
	v_cvt_pk_bf16_f32 v50, v56, v57
	v_cvt_pk_bf16_f32 v51, v58, v59
	v_cvt_pk_bf16_f32 v52, v60, v54
	v_cvt_pk_bf16_f32 v53, v55, v53
	global_store_dwordx4 v[68:69], v[50:53], off sc1
	global_load_dword v52, v[132:133], off offset:576
	s_nop 0
	v_mov_b32_e32 v50, v46
	v_mov_b32_e32 v46, v48
	v_mov_b32_e32 v48, v34
	v_mov_b32_e32 v34, v36
	v_mov_b32_e32 v51, v42
	v_mov_b32_e32 v42, v47
	v_mov_b32_e32 v47, v44
	v_mov_b32_e32 v44, v49
	v_mov_b32_e32 v49, v38
	v_mov_b32_e32 v38, v35
	v_mov_b32_e32 v35, v40
	v_mov_b32_e32 v40, v37
	v_add_u32_e32 v37, 0x90, v130
	s_waitcnt vmcnt(0)
	v_fmamk_f32 v36, v52, 0x3a800000, v131
	v_rsq_f32_e32 v36, v36
	v_mad_i64_i32 v[52:53], s[4:5], v37, s6, v[124:125]
	v_lshl_add_u64 v[52:53], v[52:53], 0, v[122:123]
	v_pk_mul_f32 v[50:51], v[50:51], v[36:37] op_sel_hi:[1,0]
	v_pk_mul_f32 v[42:43], v[42:43], v[36:37] op_sel_hi:[1,0]
	v_pk_mul_f32 v[46:47], v[46:47], v[36:37] op_sel_hi:[1,0]
	v_pk_mul_f32 v[44:45], v[44:45], v[36:37] op_sel_hi:[1,0]
	v_pk_mul_f32 v[48:49], v[48:49], v[36:37] op_sel_hi:[1,0]
	v_pk_mul_f32 v[38:39], v[38:39], v[36:37] op_sel_hi:[1,0]
	v_pk_mul_f32 v[34:35], v[34:35], v[36:37] op_sel_hi:[1,0]
	v_pk_mul_f32 v[36:37], v[40:41], v[36:37] op_sel_hi:[1,0]
	v_mul_f32_e32 v40, 0xbfb8aa3b, v51
	v_mul_f32_e32 v59, 0xbfb8aa3b, v37
	v_mul_f32_e32 v41, 0xbfb8aa3b, v43
	v_mul_f32_e32 v54, 0xbfb8aa3b, v47
	v_mul_f32_e32 v55, 0xbfb8aa3b, v45
	v_mul_f32_e32 v56, 0xbfb8aa3b, v49
	v_mul_f32_e32 v57, 0xbfb8aa3b, v39
	v_mul_f32_e32 v58, 0xbfb8aa3b, v35
	v_exp_f32_e32 v59, v59
	v_exp_f32_e32 v40, v40
	v_exp_f32_e32 v41, v41
	v_exp_f32_e32 v54, v54
	v_exp_f32_e32 v55, v55
	v_exp_f32_e32 v56, v56
	v_exp_f32_e32 v57, v57
	v_exp_f32_e32 v58, v58
	v_add_f32_e32 v59, 1.0, v59
	v_add_f32_e32 v40, 1.0, v40
	v_add_f32_e32 v41, 1.0, v41
	v_add_f32_e32 v54, 1.0, v54
	v_add_f32_e32 v55, 1.0, v55
	v_add_f32_e32 v56, 1.0, v56
	v_add_f32_e32 v57, 1.0, v57
	v_add_f32_e32 v58, 1.0, v58
	v_rcp_f32_e32 v59, v59
	v_rcp_f32_e32 v40, v40
	v_rcp_f32_e32 v41, v41
	v_rcp_f32_e32 v54, v54
	v_rcp_f32_e32 v55, v55
	v_rcp_f32_e32 v56, v56
	v_rcp_f32_e32 v57, v57
	v_rcp_f32_e32 v58, v58
	v_mul_f32_e32 v37, v37, v59
	v_mul_f32_e32 v40, v51, v40
	v_mul_f32_e32 v41, v43, v41
	v_mul_f32_e32 v43, v47, v54
	v_mul_f32_e32 v45, v45, v55
	v_mul_f32_e32 v47, v49, v56
	v_mul_f32_e32 v39, v39, v57
	v_mul_f32_e32 v35, v35, v58
	v_mul_f32_e32 v37, v36, v37
	v_mul_f32_e32 v40, v50, v40
	v_mul_f32_e32 v41, v42, v41
	v_mul_f32_e32 v42, v46, v43
	v_mul_f32_e32 v43, v44, v45
	v_mul_f32_e32 v44, v48, v47
	v_mul_f32_e32 v38, v38, v39
	v_mul_f32_e32 v39, v34, v35
	v_cvt_pk_bf16_f32 v34, v40, v41
	v_cvt_pk_bf16_f32 v35, v42, v43
	v_cvt_pk_bf16_f32 v36, v44, v38
	v_cvt_pk_bf16_f32 v37, v39, v37
	global_store_dwordx4 v[52:53], v[34:37], off sc1
	global_load_dword v36, v[132:133], off offset:640
	s_nop 0
	v_mov_b32_e32 v34, v30
	v_mov_b32_e32 v30, v32
	v_mov_b32_e32 v32, v18
	v_mov_b32_e32 v18, v20
	v_mov_b32_e32 v35, v26
	v_mov_b32_e32 v26, v31
	v_mov_b32_e32 v31, v28
	v_mov_b32_e32 v28, v33
	v_mov_b32_e32 v33, v22
	v_mov_b32_e32 v22, v19
	v_mov_b32_e32 v19, v24
	v_mov_b32_e32 v24, v21
	v_add_u32_e32 v21, 0xa0, v130
	s_waitcnt vmcnt(0)
; __device__ __forceinline__ unsigned cvt_pk_bf16(float lo, float hi) { unsigned r; asm volatile("v_cvt_pk_bf16_f32 %0, %1, %2" : "=v"(r) : "v"(lo), "v"(hi)); return r; }
; __device__ __forceinline__ float silu_f(float x) { return x * sigmoid_f(x); }
;     __device__ __forceinline__ void operator()(const f32x4 (&acc)[2][2][4][2], const Unit& u, int wr, int wc, int fr, int fq) const {
;         const int row0 = u.pm * BM + wr * 64 + fr, col0 = u.pn * 128 + wc * 32 + 8 * fq;
; #pragma unroll
;         for (int ai = 0; ai < 2; ++ai)
; #pragma unroll
;             for (int m = 0; m < 4; ++m) {
;                 const int row = row0 + ai * HALF + m * 16;
;                 const float r = __builtin_amdgcn_rsqf(rss[row] * (1.f / 1024.f) + NEPS);
;                 float o[8];
; #pragma unroll
;                 for (int n = 0; n < 2; ++n)
; #pragma unroll
;                     for (int e = 0; e < 4; ++e) o[4 * n + e] = silu_f(acc[ai][0][m][n][e] * r) * (acc[ai][1][m][n][e] * r);
;                 u32x4 w; w.x = cvt_pk_bf16(o[0], o[1]); w.y = cvt_pk_bf16(o[2], o[3]); w.z = cvt_pk_bf16(o[4], o[5]); w.w = cvt_pk_bf16(o[6], o[7]);
;                 *(u32x4*)(O + (size_t)row * 2816 + col0) = w;
	v_fmamk_f32 v20, v36, 0x3a800000, v131
	v_rsq_f32_e32 v20, v20
	v_mad_i64_i32 v[36:37], s[4:5], v21, s6, v[124:125]
	v_lshl_add_u64 v[36:37], v[36:37], 0, v[122:123]
	v_pk_mul_f32 v[34:35], v[34:35], v[20:21] op_sel_hi:[1,0]
	v_pk_mul_f32 v[26:27], v[26:27], v[20:21] op_sel_hi:[1,0]
	v_pk_mul_f32 v[30:31], v[30:31], v[20:21] op_sel_hi:[1,0]
	v_pk_mul_f32 v[28:29], v[28:29], v[20:21] op_sel_hi:[1,0]
	v_pk_mul_f32 v[32:33], v[32:33], v[20:21] op_sel_hi:[1,0]
	v_pk_mul_f32 v[22:23], v[22:23], v[20:21] op_sel_hi:[1,0]
	v_pk_mul_f32 v[18:19], v[18:19], v[20:21] op_sel_hi:[1,0]
	v_pk_mul_f32 v[20:21], v[24:25], v[20:21] op_sel_hi:[1,0]
	v_mul_f32_e32 v24, 0xbfb8aa3b, v35
	v_mul_f32_e32 v43, 0xbfb8aa3b, v21
	v_mul_f32_e32 v25, 0xbfb8aa3b, v27
	v_mul_f32_e32 v38, 0xbfb8aa3b, v31
	v_mul_f32_e32 v39, 0xbfb8aa3b, v29
	v_mul_f32_e32 v40, 0xbfb8aa3b, v33
	v_mul_f32_e32 v41, 0xbfb8aa3b, v23
	v_mul_f32_e32 v42, 0xbfb8aa3b, v19
	v_exp_f32_e32 v43, v43
	v_exp_f32_e32 v24, v24
	v_exp_f32_e32 v25, v25
	v_exp_f32_e32 v38, v38
	v_exp_f32_e32 v39, v39
	v_exp_f32_e32 v40, v40
	v_exp_f32_e32 v41, v41
	v_exp_f32_e32 v42, v42
	v_add_f32_e32 v43, 1.0, v43
	v_add_f32_e32 v24, 1.0, v24
	v_add_f32_e32 v25, 1.0, v25
	v_add_f32_e32 v38, 1.0, v38
	v_add_f32_e32 v39, 1.0, v39
	v_add_f32_e32 v40, 1.0, v40
	v_add_f32_e32 v41, 1.0, v41
	v_add_f32_e32 v42, 1.0, v42
	v_rcp_f32_e32 v43, v43
	v_rcp_f32_e32 v24, v24
	v_rcp_f32_e32 v25, v25
	v_rcp_f32_e32 v38, v38
	v_rcp_f32_e32 v39, v39
	v_rcp_f32_e32 v40, v40
	v_rcp_f32_e32 v41, v41
	v_rcp_f32_e32 v42, v42
	v_mul_f32_e32 v21, v21, v43
	v_mul_f32_e32 v24, v35, v24
	v_mul_f32_e32 v25, v27, v25
	v_mul_f32_e32 v27, v31, v38
	v_mul_f32_e32 v29, v29, v39
	v_mul_f32_e32 v31, v33, v40
	v_mul_f32_e32 v23, v23, v41
	v_mul_f32_e32 v19, v19, v42
	v_mul_f32_e32 v21, v20, v21
	v_mul_f32_e32 v24, v34, v24
	v_mul_f32_e32 v25, v26, v25
	v_mul_f32_e32 v26, v30, v27
	v_mul_f32_e32 v27, v28, v29
	v_mul_f32_e32 v28, v32, v31
	v_mul_f32_e32 v22, v22, v23
	v_mul_f32_e32 v23, v18, v19
	v_cvt_pk_bf16_f32 v18, v24, v25
	v_cvt_pk_bf16_f32 v19, v26, v27
	v_cvt_pk_bf16_f32 v20, v28, v22
	v_cvt_pk_bf16_f32 v21, v23, v21
	global_store_dwordx4 v[36:37], v[18:21], off sc1
	global_load_dword v20, v[132:133], off offset:704
	s_waitcnt vmcnt(0)
	v_fmac_f32_e32 v131, 0x3a800000, v20
	v_mov_b32_e32 v18, v14
	v_mov_b32_e32 v14, v16
	v_mov_b32_e32 v16, v2
	v_mov_b32_e32 v2, v4
	v_rsq_f32_e32 v4, v131
	v_mov_b32_e32 v19, v10
	v_mov_b32_e32 v10, v15
	v_mov_b32_e32 v15, v12
	v_mov_b32_e32 v12, v17
	v_mov_b32_e32 v17, v6
	v_mov_b32_e32 v6, v3
	v_mov_b32_e32 v3, v8
	v_mov_b32_e32 v8, v5
	v_add_u32_e32 v5, 0xb0, v130
	v_mad_i64_i32 v[20:21], s[4:5], v5, s6, v[124:125]
	v_pk_mul_f32 v[18:19], v[18:19], v[4:5] op_sel_hi:[1,0]
	v_pk_mul_f32 v[10:11], v[10:11], v[4:5] op_sel_hi:[1,0]
	v_pk_mul_f32 v[14:15], v[14:15], v[4:5] op_sel_hi:[1,0]
	v_pk_mul_f32 v[12:13], v[12:13], v[4:5] op_sel_hi:[1,0]
	v_pk_mul_f32 v[16:17], v[16:17], v[4:5] op_sel_hi:[1,0]
	v_pk_mul_f32 v[6:7], v[6:7], v[4:5] op_sel_hi:[1,0]
	v_pk_mul_f32 v[2:3], v[2:3], v[4:5] op_sel_hi:[1,0]
	v_pk_mul_f32 v[4:5], v[8:9], v[4:5] op_sel_hi:[1,0]
	v_mul_f32_e32 v25, 0xbfb8aa3b, v7
	v_mul_f32_e32 v26, 0xbfb8aa3b, v3
	v_mul_f32_e32 v27, 0xbfb8aa3b, v5
	v_mul_f32_e32 v8, 0xbfb8aa3b, v19
	v_mul_f32_e32 v9, 0xbfb8aa3b, v11
	v_mul_f32_e32 v22, 0xbfb8aa3b, v15
	v_mul_f32_e32 v23, 0xbfb8aa3b, v13
	v_mul_f32_e32 v24, 0xbfb8aa3b, v17
	v_exp_f32_e32 v25, v25
	v_exp_f32_e32 v26, v26
	v_exp_f32_e32 v27, v27
	v_exp_f32_e32 v8, v8
	v_exp_f32_e32 v9, v9
	v_exp_f32_e32 v22, v22
	v_exp_f32_e32 v23, v23
	v_exp_f32_e32 v24, v24
	v_add_f32_e32 v25, 1.0, v25
	v_add_f32_e32 v26, 1.0, v26
	v_add_f32_e32 v27, 1.0, v27
	v_add_f32_e32 v8, 1.0, v8
	v_add_f32_e32 v9, 1.0, v9
	v_add_f32_e32 v22, 1.0, v22
	v_add_f32_e32 v23, 1.0, v23
	v_add_f32_e32 v24, 1.0, v24
	v_rcp_f32_e32 v25, v25
	v_rcp_f32_e32 v26, v26
	v_rcp_f32_e32 v27, v27
	v_rcp_f32_e32 v8, v8
	v_rcp_f32_e32 v9, v9
	v_rcp_f32_e32 v22, v22
	v_rcp_f32_e32 v23, v23
	v_rcp_f32_e32 v24, v24
	v_mul_f32_e32 v7, v7, v25
	v_mul_f32_e32 v3, v3, v26
	v_mul_f32_e32 v5, v5, v27
	v_mul_f32_e32 v8, v19, v8
	v_mul_f32_e32 v9, v11, v9
	v_mul_f32_e32 v11, v15, v22
	v_mul_f32_e32 v13, v13, v23
	v_mul_f32_e32 v15, v17, v24
	v_mul_f32_e32 v6, v6, v7
	v_mul_f32_e32 v7, v2, v3
	v_mul_f32_e32 v5, v4, v5
	v_mul_f32_e32 v8, v18, v8
	v_mul_f32_e32 v9, v10, v9
	v_mul_f32_e32 v10, v14, v11
	v_mul_f32_e32 v11, v12, v13
	v_mul_f32_e32 v12, v16, v15
	v_cvt_pk_bf16_f32 v2, v8, v9
	v_cvt_pk_bf16_f32 v3, v10, v11
	v_cvt_pk_bf16_f32 v4, v12, v6
	v_cvt_pk_bf16_f32 v5, v7, v5
	v_lshl_add_u64 v[6:7], v[20:21], 0, v[122:123]
	global_store_dwordx4 v[6:7], v[2:5], off sc1
	s_waitcnt vmcnt(0)
	s_barrier
